# modulate-norm row loop: two rows prefetched ahead (alternating buffers)
# speedup vs baseline: 1.0394x; 1.0115x over previous
.Lnrm_p1_nxhave0:
	s_lshl_b32 s12, s12, 13
	s_add_u32 s14, s14, s12
	s_addc_u32 s15, s15, 0
	s_add_u32 s14, s14, 0x1000
	s_addc_u32 s15, s15, 0
	global_load_dwordx4 v[64:67], v176, s[14:15] offset:-4096
	global_load_dwordx4 v[68:71], v176, s[14:15] offset:-3072
	global_load_dwordx4 v[72:75], v176, s[14:15] offset:-2048
	global_load_dwordx4 v[76:79], v176, s[14:15] offset:-1024
	global_load_dwordx4 v[80:83], v176, s[14:15] offset:0
	global_load_dwordx4 v[84:87], v176, s[14:15] offset:1024
	global_load_dwordx4 v[88:91], v176, s[14:15] offset:2048
	global_load_dwordx4 v[92:95], v176, s[14:15] offset:3072
	s_mov_b32 s2, s3

.Lnrm_p1_advd1:
	s_mov_b32 s100, 0
	s_cmpk_lt_i32 s3, 0x2400
	s_cbranch_scc0 .Lnrm_p1_pro1
	s_mul_hi_i32 s12, s3, 0x38e38e39
	s_lshr_b32 s13, s12, 31
	s_ashr_i32 s12, s12, 9
	s_add_i32 s12, s12, s13
	s_mul_i32 s13, s12, 0xfffff700
	s_add_i32 s13, s3, s13
	s_cmpk_lt_i32 s13, 0x100
	s_cbranch_scc1 .Lnrm_p1_nxctx1
	v_readlane_b32 s14, v255, 10
	v_readlane_b32 s15, v255, 11
	s_lshl_b32 s12, s12, 11
	s_add_i32 s12, s12, s13
	s_addk_i32 s12, 0xff00
	s_branch .Lnrm_p1_nxcom1

.Lnrm_p1_nxhave1:
	s_lshl_b32 s12, s12, 13
	s_add_u32 s14, s14, s12
	s_addc_u32 s15, s15, 0
	s_add_u32 s14, s14, 0x1000
	s_addc_u32 s15, s15, 0
	global_load_dwordx4 v[32:35], v176, s[14:15] offset:-4096
	global_load_dwordx4 v[36:39], v176, s[14:15] offset:-3072
	global_load_dwordx4 v[40:43], v176, s[14:15] offset:-2048
	global_load_dwordx4 v[44:47], v176, s[14:15] offset:-1024
	global_load_dwordx4 v[48:51], v176, s[14:15] offset:0
	global_load_dwordx4 v[52:55], v176, s[14:15] offset:1024
	global_load_dwordx4 v[56:59], v176, s[14:15] offset:2048
	global_load_dwordx4 v[60:63], v176, s[14:15] offset:3072
	s_waitcnt vmcnt(8)
	s_branch .Lnrm_p1_top

.Lnrm_p1_top:
	s_bitcmp1_b32 s100, 8
	s_cbranch_scc1 .Lnrm_p1_cpB
	v_mov_b64_e32 v[0:1], v[64:65]
	v_mov_b64_e32 v[2:3], v[66:67]
	v_mov_b64_e32 v[4:5], v[68:69]
	v_mov_b64_e32 v[6:7], v[70:71]
	v_mov_b64_e32 v[8:9], v[72:73]
	v_mov_b64_e32 v[10:11], v[74:75]
	v_mov_b64_e32 v[12:13], v[76:77]
	v_mov_b64_e32 v[14:15], v[78:79]
	v_mov_b64_e32 v[16:17], v[80:81]
	v_mov_b64_e32 v[18:19], v[82:83]
	v_mov_b64_e32 v[20:21], v[84:85]
	v_mov_b64_e32 v[22:23], v[86:87]
	v_mov_b64_e32 v[24:25], v[88:89]
	v_mov_b64_e32 v[26:27], v[90:91]
	v_mov_b64_e32 v[28:29], v[92:93]
	v_mov_b64_e32 v[30:31], v[94:95]
	s_branch .Lnrm_p1_cpD
.Lnrm_p1_cpB:
	v_mov_b64_e32 v[0:1], v[32:33]
	v_mov_b64_e32 v[2:3], v[34:35]
	v_mov_b64_e32 v[4:5], v[36:37]
	v_mov_b64_e32 v[6:7], v[38:39]
	v_mov_b64_e32 v[8:9], v[40:41]
	v_mov_b64_e32 v[10:11], v[42:43]
	v_mov_b64_e32 v[12:13], v[44:45]
	v_mov_b64_e32 v[14:15], v[46:47]
	v_mov_b64_e32 v[16:17], v[48:49]
	v_mov_b64_e32 v[18:19], v[50:51]
	v_mov_b64_e32 v[20:21], v[52:53]
	v_mov_b64_e32 v[22:23], v[54:55]
	v_mov_b64_e32 v[24:25], v[56:57]
	v_mov_b64_e32 v[26:27], v[58:59]
	v_mov_b64_e32 v[28:29], v[60:61]
	v_mov_b64_e32 v[30:31], v[62:63]
.Lnrm_p1_cpD:
	s_mul_hi_i32 s4, s2, 0x38e38e39
	s_lshr_b32 s5, s4, 31
	s_ashr_i32 s4, s4, 9
	s_add_i32 s4, s4, s5
	s_mul_i32 s5, s4, 0xfffff700
	s_add_i32 s5, s2, s5
	s_cmpk_lt_i32 s5, 0x100
	s_cselect_b32 s8, 1, 0
	s_and_b32 s100, s100, 0x100
	s_or_b32 s100, s100, s8
	v_readlane_b32 s9, v255, 18
	s_and_b32 s8, s8, s9
	s_cmp_lg_u32 s8, 0
	s_cbranch_scc0 .Lnrm_p1_nopart
	v_readlane_b32 s12, v255, 14
	v_readlane_b32 s13, v255, 15
	s_lshl_b32 s8, s4, 8
	s_add_i32 s8, s8, s5
	s_lshl_b32 s8, s8, 13
	s_add_u32 s12, s12, s8
	s_addc_u32 s13, s13, 0
	s_add_u32 s12, s12, 0x1000
	s_addc_u32 s13, s13, 0
	v_readlane_b32 s10, v255, 16
	v_readlane_b32 s11, v255, 17
	s_nop 0
	s_add_u32 s10, s10, 0x1000
	s_addc_u32 s11, s11, 0
	s_lshl_b32 s8, s2, 13
	s_add_u32 s8, s8, 0xb601000
	s_add_u32 s8, s54, s8
	s_addc_u32 s9, s55, 0
	s_mov_b64 s[14:15], s[12:13]
	global_load_dwordx4 v[96:99], v176, s[14:15] offset:-4096
	global_load_dwordx4 v[128:131], v176, s[14:15] offset:-3072
	s_add_u32 s14, s14, 0x800000
	s_addc_u32 s15, s15, 0
	global_load_dwordx4 v[100:103], v176, s[14:15] offset:-4096
	global_load_dwordx4 v[132:135], v176, s[14:15] offset:-3072
	s_add_u32 s14, s14, 0x800000
	s_addc_u32 s15, s15, 0
	global_load_dwordx4 v[104:107], v176, s[14:15] offset:-4096
	global_load_dwordx4 v[136:139], v176, s[14:15] offset:-3072
	s_add_u32 s14, s14, 0x800000
	s_addc_u32 s15, s15, 0
	global_load_dwordx4 v[108:111], v176, s[14:15] offset:-4096
	global_load_dwordx4 v[140:143], v176, s[14:15] offset:-3072
	s_add_u32 s14, s14, 0x800000
	s_addc_u32 s15, s15, 0
	global_load_dwordx4 v[112:115], v176, s[14:15] offset:-4096
	global_load_dwordx4 v[144:147], v176, s[14:15] offset:-3072
	s_add_u32 s14, s14, 0x800000
	s_addc_u32 s15, s15, 0
	global_load_dwordx4 v[116:119], v176, s[14:15] offset:-4096
	global_load_dwordx4 v[148:151], v176, s[14:15] offset:-3072
	s_add_u32 s14, s14, 0x800000
	s_addc_u32 s15, s15, 0
	global_load_dwordx4 v[120:123], v176, s[14:15] offset:-4096
	global_load_dwordx4 v[152:155], v176, s[14:15] offset:-3072
	s_add_u32 s14, s14, 0x800000
	s_addc_u32 s15, s15, 0
	global_load_dwordx4 v[124:127], v176, s[14:15] offset:-4096
	global_load_dwordx4 v[156:159], v176, s[14:15] offset:-3072
	global_load_dwordx4 v[160:163], v176, s[10:11] offset:-4096
	global_load_dwordx4 v[164:167], v176, s[10:11] offset:-3072
	s_waitcnt vmcnt(0)
	v_pk_add_f32 v[96:97], v[96:97], v[100:101]
	v_pk_add_f32 v[98:99], v[98:99], v[102:103]
	v_pk_add_f32 v[96:97], v[96:97], v[104:105]
	v_pk_add_f32 v[98:99], v[98:99], v[106:107]
	v_pk_add_f32 v[96:97], v[96:97], v[108:109]
	v_pk_add_f32 v[98:99], v[98:99], v[110:111]
	v_pk_add_f32 v[96:97], v[96:97], v[112:113]
	v_pk_add_f32 v[98:99], v[98:99], v[114:115]
	v_pk_add_f32 v[96:97], v[96:97], v[116:117]
	v_pk_add_f32 v[98:99], v[98:99], v[118:119]
	v_pk_add_f32 v[96:97], v[96:97], v[120:121]
	v_pk_add_f32 v[98:99], v[98:99], v[122:123]
	v_pk_add_f32 v[96:97], v[96:97], v[124:125]
	v_pk_add_f32 v[98:99], v[98:99], v[126:127]
	v_pk_add_f32 v[128:129], v[128:129], v[132:133]
	v_pk_add_f32 v[130:131], v[130:131], v[134:135]
	v_pk_add_f32 v[128:129], v[128:129], v[136:137]
	v_pk_add_f32 v[130:131], v[130:131], v[138:139]
	v_pk_add_f32 v[128:129], v[128:129], v[140:141]
	v_pk_add_f32 v[130:131], v[130:131], v[142:143]
	v_pk_add_f32 v[128:129], v[128:129], v[144:145]
	v_pk_add_f32 v[130:131], v[130:131], v[146:147]
	v_pk_add_f32 v[128:129], v[128:129], v[148:149]
	v_pk_add_f32 v[130:131], v[130:131], v[150:151]
	v_pk_add_f32 v[128:129], v[128:129], v[152:153]
	v_pk_add_f32 v[130:131], v[130:131], v[154:155]
	v_pk_add_f32 v[128:129], v[128:129], v[156:157]
	v_pk_add_f32 v[130:131], v[130:131], v[158:159]
	v_pk_fma_f32 v[0:1], v[96:97], v[160:161], v[0:1]
	v_pk_fma_f32 v[2:3], v[98:99], v[162:163], v[2:3]
	v_pk_fma_f32 v[4:5], v[128:129], v[164:165], v[4:5]
	v_pk_fma_f32 v[6:7], v[130:131], v[166:167], v[6:7]
	global_store_dwordx4 v176, v[0:3], s[8:9] offset:-4096
	global_store_dwordx4 v176, v[4:7], s[8:9] offset:-3072
	s_mov_b64 s[14:15], s[12:13]
	global_load_dwordx4 v[96:99], v176, s[14:15] offset:-2048
	global_load_dwordx4 v[128:131], v176, s[14:15] offset:-1024
	s_add_u32 s14, s14, 0x800000
	s_addc_u32 s15, s15, 0
	global_load_dwordx4 v[100:103], v176, s[14:15] offset:-2048
	global_load_dwordx4 v[132:135], v176, s[14:15] offset:-1024
	s_add_u32 s14, s14, 0x800000
	s_addc_u32 s15, s15, 0
	global_load_dwordx4 v[104:107], v176, s[14:15] offset:-2048
	global_load_dwordx4 v[136:139], v176, s[14:15] offset:-1024
	s_add_u32 s14, s14, 0x800000
	s_addc_u32 s15, s15, 0
	global_load_dwordx4 v[108:111], v176, s[14:15] offset:-2048
	global_load_dwordx4 v[140:143], v176, s[14:15] offset:-1024
	s_add_u32 s14, s14, 0x800000
	s_addc_u32 s15, s15, 0
	global_load_dwordx4 v[112:115], v176, s[14:15] offset:-2048
	global_load_dwordx4 v[144:147], v176, s[14:15] offset:-1024
	s_add_u32 s14, s14, 0x800000
	s_addc_u32 s15, s15, 0
	global_load_dwordx4 v[116:119], v176, s[14:15] offset:-2048
	global_load_dwordx4 v[148:151], v176, s[14:15] offset:-1024
	s_add_u32 s14, s14, 0x800000
	s_addc_u32 s15, s15, 0
	global_load_dwordx4 v[120:123], v176, s[14:15] offset:-2048
	global_load_dwordx4 v[152:155], v176, s[14:15] offset:-1024
	s_add_u32 s14, s14, 0x800000
	s_addc_u32 s15, s15, 0
	global_load_dwordx4 v[124:127], v176, s[14:15] offset:-2048
	global_load_dwordx4 v[156:159], v176, s[14:15] offset:-1024
	global_load_dwordx4 v[160:163], v176, s[10:11] offset:-2048
	global_load_dwordx4 v[164:167], v176, s[10:11] offset:-1024
	s_waitcnt vmcnt(0)
	v_pk_add_f32 v[96:97], v[96:97], v[100:101]
	v_pk_add_f32 v[98:99], v[98:99], v[102:103]
	v_pk_add_f32 v[96:97], v[96:97], v[104:105]
	v_pk_add_f32 v[98:99], v[98:99], v[106:107]
	v_pk_add_f32 v[96:97], v[96:97], v[108:109]
	v_pk_add_f32 v[98:99], v[98:99], v[110:111]
	v_pk_add_f32 v[96:97], v[96:97], v[112:113]
	v_pk_add_f32 v[98:99], v[98:99], v[114:115]
	v_pk_add_f32 v[96:97], v[96:97], v[116:117]
	v_pk_add_f32 v[98:99], v[98:99], v[118:119]
	v_pk_add_f32 v[96:97], v[96:97], v[120:121]
	v_pk_add_f32 v[98:99], v[98:99], v[122:123]
	v_pk_add_f32 v[96:97], v[96:97], v[124:125]
	v_pk_add_f32 v[98:99], v[98:99], v[126:127]
	v_pk_add_f32 v[128:129], v[128:129], v[132:133]
	v_pk_add_f32 v[130:131], v[130:131], v[134:135]
	v_pk_add_f32 v[128:129], v[128:129], v[136:137]
	v_pk_add_f32 v[130:131], v[130:131], v[138:139]
	v_pk_add_f32 v[128:129], v[128:129], v[140:141]
	v_pk_add_f32 v[130:131], v[130:131], v[142:143]
	v_pk_add_f32 v[128:129], v[128:129], v[144:145]
	v_pk_add_f32 v[130:131], v[130:131], v[146:147]
	v_pk_add_f32 v[128:129], v[128:129], v[148:149]
	v_pk_add_f32 v[130:131], v[130:131], v[150:151]
	v_pk_add_f32 v[128:129], v[128:129], v[152:153]
	v_pk_add_f32 v[130:131], v[130:131], v[154:155]
	v_pk_add_f32 v[128:129], v[128:129], v[156:157]
	v_pk_add_f32 v[130:131], v[130:131], v[158:159]
	v_pk_fma_f32 v[8:9], v[96:97], v[160:161], v[8:9]
	v_pk_fma_f32 v[10:11], v[98:99], v[162:163], v[10:11]
	v_pk_fma_f32 v[12:13], v[128:129], v[164:165], v[12:13]
	v_pk_fma_f32 v[14:15], v[130:131], v[166:167], v[14:15]
	global_store_dwordx4 v176, v[8:11], s[8:9] offset:-2048
	global_store_dwordx4 v176, v[12:15], s[8:9] offset:-1024
	s_mov_b64 s[14:15], s[12:13]
	global_load_dwordx4 v[96:99], v176, s[14:15] offset:0
	global_load_dwordx4 v[128:131], v176, s[14:15] offset:1024
	s_add_u32 s14, s14, 0x800000
	s_addc_u32 s15, s15, 0
	global_load_dwordx4 v[100:103], v176, s[14:15] offset:0
	global_load_dwordx4 v[132:135], v176, s[14:15] offset:1024
	s_add_u32 s14, s14, 0x800000
	s_addc_u32 s15, s15, 0
	global_load_dwordx4 v[104:107], v176, s[14:15] offset:0
	global_load_dwordx4 v[136:139], v176, s[14:15] offset:1024
	s_add_u32 s14, s14, 0x800000
	s_addc_u32 s15, s15, 0
	global_load_dwordx4 v[108:111], v176, s[14:15] offset:0
	global_load_dwordx4 v[140:143], v176, s[14:15] offset:1024
	s_add_u32 s14, s14, 0x800000
	s_addc_u32 s15, s15, 0
	global_load_dwordx4 v[112:115], v176, s[14:15] offset:0
	global_load_dwordx4 v[144:147], v176, s[14:15] offset:1024
	s_add_u32 s14, s14, 0x800000
	s_addc_u32 s15, s15, 0
	global_load_dwordx4 v[116:119], v176, s[14:15] offset:0
	global_load_dwordx4 v[148:151], v176, s[14:15] offset:1024
	s_add_u32 s14, s14, 0x800000
	s_addc_u32 s15, s15, 0
	global_load_dwordx4 v[120:123], v176, s[14:15] offset:0
	global_load_dwordx4 v[152:155], v176, s[14:15] offset:1024
	s_add_u32 s14, s14, 0x800000
	s_addc_u32 s15, s15, 0
	global_load_dwordx4 v[124:127], v176, s[14:15] offset:0
	global_load_dwordx4 v[156:159], v176, s[14:15] offset:1024
	global_load_dwordx4 v[160:163], v176, s[10:11] offset:0
	global_load_dwordx4 v[164:167], v176, s[10:11] offset:1024
	s_waitcnt vmcnt(0)
	v_pk_add_f32 v[96:97], v[96:97], v[100:101]
	v_pk_add_f32 v[98:99], v[98:99], v[102:103]
	v_pk_add_f32 v[96:97], v[96:97], v[104:105]
	v_pk_add_f32 v[98:99], v[98:99], v[106:107]
	v_pk_add_f32 v[96:97], v[96:97], v[108:109]
	v_pk_add_f32 v[98:99], v[98:99], v[110:111]
	v_pk_add_f32 v[96:97], v[96:97], v[112:113]
	v_pk_add_f32 v[98:99], v[98:99], v[114:115]
	v_pk_add_f32 v[96:97], v[96:97], v[116:117]
	v_pk_add_f32 v[98:99], v[98:99], v[118:119]
	v_pk_add_f32 v[96:97], v[96:97], v[120:121]
	v_pk_add_f32 v[98:99], v[98:99], v[122:123]
	v_pk_add_f32 v[96:97], v[96:97], v[124:125]
	v_pk_add_f32 v[98:99], v[98:99], v[126:127]
	v_pk_add_f32 v[128:129], v[128:129], v[132:133]
	v_pk_add_f32 v[130:131], v[130:131], v[134:135]
	v_pk_add_f32 v[128:129], v[128:129], v[136:137]
	v_pk_add_f32 v[130:131], v[130:131], v[138:139]
	v_pk_add_f32 v[128:129], v[128:129], v[140:141]
	v_pk_add_f32 v[130:131], v[130:131], v[142:143]
	v_pk_add_f32 v[128:129], v[128:129], v[144:145]
	v_pk_add_f32 v[130:131], v[130:131], v[146:147]
	v_pk_add_f32 v[128:129], v[128:129], v[148:149]
	v_pk_add_f32 v[130:131], v[130:131], v[150:151]
	v_pk_add_f32 v[128:129], v[128:129], v[152:153]
	v_pk_add_f32 v[130:131], v[130:131], v[154:155]
	v_pk_add_f32 v[128:129], v[128:129], v[156:157]
	v_pk_add_f32 v[130:131], v[130:131], v[158:159]
	v_pk_fma_f32 v[16:17], v[96:97], v[160:161], v[16:17]
	v_pk_fma_f32 v[18:19], v[98:99], v[162:163], v[18:19]
	v_pk_fma_f32 v[20:21], v[128:129], v[164:165], v[20:21]
	v_pk_fma_f32 v[22:23], v[130:131], v[166:167], v[22:23]
	global_store_dwordx4 v176, v[16:19], s[8:9] offset:0
	global_store_dwordx4 v176, v[20:23], s[8:9] offset:1024
	s_mov_b64 s[14:15], s[12:13]
	global_load_dwordx4 v[96:99], v176, s[14:15] offset:2048
	global_load_dwordx4 v[128:131], v176, s[14:15] offset:3072
	s_add_u32 s14, s14, 0x800000
	s_addc_u32 s15, s15, 0
	global_load_dwordx4 v[100:103], v176, s[14:15] offset:2048
	global_load_dwordx4 v[132:135], v176, s[14:15] offset:3072
	s_add_u32 s14, s14, 0x800000
	s_addc_u32 s15, s15, 0
	global_load_dwordx4 v[104:107], v176, s[14:15] offset:2048
	global_load_dwordx4 v[136:139], v176, s[14:15] offset:3072
	s_add_u32 s14, s14, 0x800000
	s_addc_u32 s15, s15, 0
	global_load_dwordx4 v[108:111], v176, s[14:15] offset:2048
	global_load_dwordx4 v[140:143], v176, s[14:15] offset:3072
	s_add_u32 s14, s14, 0x800000
	s_addc_u32 s15, s15, 0
	global_load_dwordx4 v[112:115], v176, s[14:15] offset:2048
	global_load_dwordx4 v[144:147], v176, s[14:15] offset:3072
	s_add_u32 s14, s14, 0x800000
	s_addc_u32 s15, s15, 0
	global_load_dwordx4 v[116:119], v176, s[14:15] offset:2048
	global_load_dwordx4 v[148:151], v176, s[14:15] offset:3072
	s_add_u32 s14, s14, 0x800000
	s_addc_u32 s15, s15, 0
	global_load_dwordx4 v[120:123], v176, s[14:15] offset:2048
	global_load_dwordx4 v[152:155], v176, s[14:15] offset:3072
	s_add_u32 s14, s14, 0x800000
	s_addc_u32 s15, s15, 0
	global_load_dwordx4 v[124:127], v176, s[14:15] offset:2048
	global_load_dwordx4 v[156:159], v176, s[14:15] offset:3072
	global_load_dwordx4 v[160:163], v176, s[10:11] offset:2048
	global_load_dwordx4 v[164:167], v176, s[10:11] offset:3072
	s_waitcnt vmcnt(0)
	v_pk_add_f32 v[96:97], v[96:97], v[100:101]
	v_pk_add_f32 v[98:99], v[98:99], v[102:103]
	v_pk_add_f32 v[96:97], v[96:97], v[104:105]
	v_pk_add_f32 v[98:99], v[98:99], v[106:107]
	v_pk_add_f32 v[96:97], v[96:97], v[108:109]
	v_pk_add_f32 v[98:99], v[98:99], v[110:111]
	v_pk_add_f32 v[96:97], v[96:97], v[112:113]
	v_pk_add_f32 v[98:99], v[98:99], v[114:115]
	v_pk_add_f32 v[96:97], v[96:97], v[116:117]
	v_pk_add_f32 v[98:99], v[98:99], v[118:119]
	v_pk_add_f32 v[96:97], v[96:97], v[120:121]
	v_pk_add_f32 v[98:99], v[98:99], v[122:123]
	v_pk_add_f32 v[96:97], v[96:97], v[124:125]
	v_pk_add_f32 v[98:99], v[98:99], v[126:127]
	v_pk_add_f32 v[128:129], v[128:129], v[132:133]
	v_pk_add_f32 v[130:131], v[130:131], v[134:135]
	v_pk_add_f32 v[128:129], v[128:129], v[136:137]
	v_pk_add_f32 v[130:131], v[130:131], v[138:139]
	v_pk_add_f32 v[128:129], v[128:129], v[140:141]
	v_pk_add_f32 v[130:131], v[130:131], v[142:143]
	v_pk_add_f32 v[128:129], v[128:129], v[144:145]
	v_pk_add_f32 v[130:131], v[130:131], v[146:147]
	v_pk_add_f32 v[128:129], v[128:129], v[148:149]
	v_pk_add_f32 v[130:131], v[130:131], v[150:151]
	v_pk_add_f32 v[128:129], v[128:129], v[152:153]
	v_pk_add_f32 v[130:131], v[130:131], v[154:155]
	v_pk_add_f32 v[128:129], v[128:129], v[156:157]
	v_pk_add_f32 v[130:131], v[130:131], v[158:159]
	v_pk_fma_f32 v[24:25], v[96:97], v[160:161], v[24:25]
	v_pk_fma_f32 v[26:27], v[98:99], v[162:163], v[26:27]
	v_pk_fma_f32 v[28:29], v[128:129], v[164:165], v[28:29]
	v_pk_fma_f32 v[30:31], v[130:131], v[166:167], v[30:31]
	global_store_dwordx4 v176, v[24:27], s[8:9] offset:2048
	global_store_dwordx4 v176, v[28:31], s[8:9] offset:3072
.Lnrm_p1_nopart:
	s_bitcmp1_b32 s100, 0
	s_cselect_b32 s8, 4, s4
	v_readlane_b32 s10, v254, 53
	v_readlane_b32 s11, v254, 54
	s_mul_i32 s8, s8, 0xc000
	s_add_u32 s10, s10, s8
	s_addc_u32 s11, s11, 0
	s_add_u32 s12, s10, 0x1000
	s_addc_u32 s13, s11, 0
	global_load_dwordx4 v[96:99], v176, s[12:13] offset:-4096
	global_load_dwordx4 v[100:103], v176, s[12:13] offset:-3072
	global_load_dwordx4 v[104:107], v176, s[12:13] offset:-2048
	global_load_dwordx4 v[108:111], v176, s[12:13] offset:-1024
	global_load_dwordx4 v[112:115], v176, s[12:13] offset:0
	global_load_dwordx4 v[116:119], v176, s[12:13] offset:1024
	global_load_dwordx4 v[120:123], v176, s[12:13] offset:2048
	global_load_dwordx4 v[124:127], v176, s[12:13] offset:3072
	s_add_u32 s12, s10, 0x3000
	s_addc_u32 s13, s11, 0
	global_load_dwordx4 v[128:131], v176, s[12:13] offset:-4096
	global_load_dwordx4 v[132:135], v176, s[12:13] offset:-3072
	global_load_dwordx4 v[136:139], v176, s[12:13] offset:-2048
	global_load_dwordx4 v[140:143], v176, s[12:13] offset:-1024
	global_load_dwordx4 v[144:147], v176, s[12:13] offset:0
	global_load_dwordx4 v[148:151], v176, s[12:13] offset:1024
	global_load_dwordx4 v[152:155], v176, s[12:13] offset:2048
	global_load_dwordx4 v[156:159], v176, s[12:13] offset:3072
	s_mov_b32 s101, s3
.Lnrm_p1_adv2:
	s_add_i32 s101, s101, s88
	s_cmpk_lt_i32 s101, 0x2400
	s_cbranch_scc0 .Lnrm_p1_advd2
.Lnrm_p1_advd2:
	s_cmpk_lt_i32 s101, 0x2400
	s_cbranch_scc0 .Lnrm_p1_nonext
	s_bitcmp1_b32 s100, 8
	s_cbranch_scc1 .Lnrm_p1_pfB
	s_mul_hi_i32 s12, s101, 0x38e38e39
	s_lshr_b32 s13, s12, 31
	s_ashr_i32 s12, s12, 9
	s_add_i32 s12, s12, s13
	s_mul_i32 s13, s12, 0xfffff700
	s_add_i32 s13, s101, s13
	s_cmpk_lt_i32 s13, 0x100
	s_cbranch_scc1 .Lnrm_p1_nxctx2
	v_readlane_b32 s14, v255, 10
	v_readlane_b32 s15, v255, 11
	s_lshl_b32 s12, s12, 11
	s_add_i32 s12, s12, s13
	s_addk_i32 s12, 0xff00
	s_branch .Lnrm_p1_nxcom2

.Lnrm_p1_nxcom2:
	s_cmp_eq_u64 s[14:15], 0
	s_cbranch_scc0 .Lnrm_p1_nxhave2
	s_add_u32 s14, s54, 0xb600000
	s_addc_u32 s15, s55, 0
	s_mov_b32 s12, s101
.Lnrm_p1_nxhave2:
	s_lshl_b32 s12, s12, 13
	s_add_u32 s14, s14, s12
	s_addc_u32 s15, s15, 0
	s_add_u32 s14, s14, 0x1000
	s_addc_u32 s15, s15, 0
	global_load_dwordx4 v[64:67], v176, s[14:15] offset:-4096
	global_load_dwordx4 v[68:71], v176, s[14:15] offset:-3072
	global_load_dwordx4 v[72:75], v176, s[14:15] offset:-2048
	global_load_dwordx4 v[76:79], v176, s[14:15] offset:-1024
	global_load_dwordx4 v[80:83], v176, s[14:15] offset:0
	global_load_dwordx4 v[84:87], v176, s[14:15] offset:1024
	global_load_dwordx4 v[88:91], v176, s[14:15] offset:2048
	global_load_dwordx4 v[92:95], v176, s[14:15] offset:3072
	s_branch .Lnrm_p1_nonext
.Lnrm_p1_pfB:
	s_mul_hi_i32 s12, s101, 0x38e38e39
	s_lshr_b32 s13, s12, 31
	s_ashr_i32 s12, s12, 9
	s_add_i32 s12, s12, s13
	s_mul_i32 s13, s12, 0xfffff700
	s_add_i32 s13, s101, s13
	s_cmpk_lt_i32 s13, 0x100
	s_cbranch_scc1 .Lnrm_p1_nxctx3
	v_readlane_b32 s14, v255, 10
	v_readlane_b32 s15, v255, 11
	s_lshl_b32 s12, s12, 11
	s_add_i32 s12, s12, s13
	s_addk_i32 s12, 0xff00
	s_branch .Lnrm_p1_nxcom3

.Lnrm_p1_nxhave3:
	s_lshl_b32 s12, s12, 13
	s_add_u32 s14, s14, s12
	s_addc_u32 s15, s15, 0
	s_add_u32 s14, s14, 0x1000
	s_addc_u32 s15, s15, 0
	global_load_dwordx4 v[32:35], v176, s[14:15] offset:-4096
	global_load_dwordx4 v[36:39], v176, s[14:15] offset:-3072
	global_load_dwordx4 v[40:43], v176, s[14:15] offset:-2048
	global_load_dwordx4 v[44:47], v176, s[14:15] offset:-1024
	global_load_dwordx4 v[48:51], v176, s[14:15] offset:0
	global_load_dwordx4 v[52:55], v176, s[14:15] offset:1024
	global_load_dwordx4 v[56:59], v176, s[14:15] offset:2048
	global_load_dwordx4 v[60:63], v176, s[14:15] offset:3072
.Lnrm_p1_nonext:
	v_mul_f32_e32 v160, v0, v0
	v_mul_f32_e32 v161, v1, v1
	v_mul_f32_e32 v162, v2, v2
	v_mul_f32_e32 v163, v3, v3
	v_fmac_f32_e32 v160, v4, v4
	v_fmac_f32_e32 v161, v5, v5
	v_fmac_f32_e32 v162, v6, v6
	v_fmac_f32_e32 v163, v7, v7
	v_fmac_f32_e32 v160, v8, v8
	v_fmac_f32_e32 v161, v9, v9
	v_fmac_f32_e32 v162, v10, v10
	v_fmac_f32_e32 v163, v11, v11
	v_fmac_f32_e32 v160, v12, v12
	v_fmac_f32_e32 v161, v13, v13
	v_fmac_f32_e32 v162, v14, v14
	v_fmac_f32_e32 v163, v15, v15
	v_fmac_f32_e32 v160, v16, v16
	v_fmac_f32_e32 v161, v17, v17
	v_fmac_f32_e32 v162, v18, v18
	v_fmac_f32_e32 v163, v19, v19
	v_fmac_f32_e32 v160, v20, v20
	v_fmac_f32_e32 v161, v21, v21
	v_fmac_f32_e32 v162, v22, v22
	v_fmac_f32_e32 v163, v23, v23
	v_fmac_f32_e32 v160, v24, v24
	v_fmac_f32_e32 v161, v25, v25
	v_fmac_f32_e32 v162, v26, v26
	v_fmac_f32_e32 v163, v27, v27
	v_fmac_f32_e32 v160, v28, v28
	v_fmac_f32_e32 v161, v29, v29
	v_fmac_f32_e32 v162, v30, v30
	v_fmac_f32_e32 v163, v31, v31
	v_add_f32_e32 v160, v160, v161
	v_add_f32_e32 v162, v162, v163
	v_add_f32_e32 v160, v160, v162
	s_nop 1
	v_add_f32_dpp v160, v160, v160 quad_perm:[1,0,3,2] row_mask:0xf bank_mask:0xf
	s_nop 1
	v_add_f32_dpp v160, v160, v160 quad_perm:[2,3,0,1] row_mask:0xf bank_mask:0xf
	s_nop 1
	v_add_f32_dpp v160, v160, v160 row_half_mirror row_mask:0xf bank_mask:0xf
	s_nop 1
	v_add_f32_dpp v160, v160, v160 row_mirror row_mask:0xf bank_mask:0xf
	s_nop 1
	v_mov_b32_e32 v161, v160
	s_nop 1
	v_permlane16_swap_b32_e32 v160, v161
	s_nop 1
	v_add_f32_e32 v160, v160, v161
	v_mov_b32_e32 v161, v160
	s_nop 1
	v_permlane32_swap_b32_e32 v160, v161
	s_nop 1
	v_add_f32_e32 v164, v160, v161
	v_fmamk_f32 v164, v164, 0x3a000000, v215
	v_mul_f32_e32 v165, 0x4f800000, v164
	v_cmp_gt_f32_e32 vcc, 0xf800000, v164
	s_nop 1
	v_cndmask_b32_e32 v164, v164, v165, vcc
	v_sqrt_f32_e32 v165, v164
	s_nop 0
	v_add_u32_e32 v166, -1, v165
	v_fma_f32 v167, -v166, v165, v164
	v_cmp_ge_f32_e64 s[14:15], 0, v167
	v_add_u32_e32 v167, 1, v165
	s_nop 0
	v_cndmask_b32_e64 v166, v165, v166, s[14:15]
	v_fma_f32 v165, -v167, v165, v164
	v_cmp_lt_f32_e64 s[14:15], 0, v165
	s_nop 1
	v_cndmask_b32_e64 v165, v166, v167, s[14:15]
	v_mul_f32_e32 v166, 0x37800000, v165
	v_cndmask_b32_e32 v165, v165, v166, vcc
	v_cmp_class_f32_e32 vcc, v164, v216
	s_nop 1
	v_cndmask_b32_e32 v164, v165, v164, vcc
	v_div_scale_f32 v165, s[14:15], v164, v164, 1.0
	v_rcp_f32_e32 v166, v165
	s_nop 1
	v_fma_f32 v167, -v165, v166, 1.0
	v_fmac_f32_e32 v166, v167, v166
	v_div_scale_f32 v167, vcc, 1.0, v164, 1.0
	v_mul_f32_e32 v168, v167, v166
	v_fma_f32 v169, -v165, v168, v167
	v_fmac_f32_e32 v168, v169, v166
	v_fma_f32 v165, -v165, v168, v167
	s_nop 0
	v_div_fmas_f32 v165, v165, v166, v168
	v_div_fixup_f32 v164, v165, v164, 1.0
	v_pk_mul_f32 v[0:1], v[0:1], v[164:165] op_sel_hi:[1,0]
	v_pk_mul_f32 v[2:3], v[2:3], v[164:165] op_sel_hi:[1,0]
	v_pk_mul_f32 v[4:5], v[4:5], v[164:165] op_sel_hi:[1,0]
	v_pk_mul_f32 v[6:7], v[6:7], v[164:165] op_sel_hi:[1,0]
	v_pk_mul_f32 v[8:9], v[8:9], v[164:165] op_sel_hi:[1,0]
	v_pk_mul_f32 v[10:11], v[10:11], v[164:165] op_sel_hi:[1,0]
	v_pk_mul_f32 v[12:13], v[12:13], v[164:165] op_sel_hi:[1,0]
	v_pk_mul_f32 v[14:15], v[14:15], v[164:165] op_sel_hi:[1,0]
	v_pk_mul_f32 v[16:17], v[16:17], v[164:165] op_sel_hi:[1,0]
	v_pk_mul_f32 v[18:19], v[18:19], v[164:165] op_sel_hi:[1,0]
	v_pk_mul_f32 v[20:21], v[20:21], v[164:165] op_sel_hi:[1,0]
	v_pk_mul_f32 v[22:23], v[22:23], v[164:165] op_sel_hi:[1,0]
	v_pk_mul_f32 v[24:25], v[24:25], v[164:165] op_sel_hi:[1,0]
	v_pk_mul_f32 v[26:27], v[26:27], v[164:165] op_sel_hi:[1,0]
	v_pk_mul_f32 v[28:29], v[28:29], v[164:165] op_sel_hi:[1,0]
	v_pk_mul_f32 v[30:31], v[30:31], v[164:165] op_sel_hi:[1,0]
	s_lshl_b32 s8, s2, 12
	s_add_u32 s8, s8, 0xfe00000
	s_add_u32 s8, s54, s8
	s_addc_u32 s9, s55, 0
	s_cmpk_lt_i32 s101, 0x2400
	s_cbranch_scc1 .Lnrm_p1_w8
	s_waitcnt vmcnt(0)
	s_branch .Lnrm_p1_wd

.Lnrm_p1_wd:
	v_pk_mul_f32 v[0:1], v[178:179], v[0:1]
	v_pk_add_f32 v[172:173], v[128:129], 1.0 op_sel_hi:[1,0]
	v_pk_fma_f32 v[0:1], v[172:173], v[0:1], v[96:97]
	v_pk_mul_f32 v[2:3], v[180:181], v[2:3]
	v_pk_add_f32 v[174:175], v[130:131], 1.0 op_sel_hi:[1,0]
	v_pk_fma_f32 v[2:3], v[174:175], v[2:3], v[98:99]
	v_cvt_pk_bf16_f32 v168, v0, v1
	v_cvt_pk_bf16_f32 v169, v2, v3
	global_store_dwordx2 v210, v[168:169], s[8:9] offset:0
	s_nop 0
	v_pk_mul_f32 v[4:5], v[182:183], v[4:5]
	v_pk_add_f32 v[172:173], v[132:133], 1.0 op_sel_hi:[1,0]
	v_pk_fma_f32 v[4:5], v[172:173], v[4:5], v[100:101]
	v_pk_mul_f32 v[6:7], v[184:185], v[6:7]
	v_pk_add_f32 v[174:175], v[134:135], 1.0 op_sel_hi:[1,0]
	v_pk_fma_f32 v[6:7], v[174:175], v[6:7], v[102:103]
	v_cvt_pk_bf16_f32 v168, v4, v5
	v_cvt_pk_bf16_f32 v169, v6, v7
	global_store_dwordx2 v210, v[168:169], s[8:9] offset:512
	s_nop 0
	v_pk_mul_f32 v[8:9], v[186:187], v[8:9]
	v_pk_add_f32 v[172:173], v[136:137], 1.0 op_sel_hi:[1,0]
	v_pk_fma_f32 v[8:9], v[172:173], v[8:9], v[104:105]
	v_pk_mul_f32 v[10:11], v[188:189], v[10:11]
	v_pk_add_f32 v[174:175], v[138:139], 1.0 op_sel_hi:[1,0]
	v_pk_fma_f32 v[10:11], v[174:175], v[10:11], v[106:107]
	v_cvt_pk_bf16_f32 v168, v8, v9
	v_cvt_pk_bf16_f32 v169, v10, v11
	global_store_dwordx2 v210, v[168:169], s[8:9] offset:1024
	s_nop 0
	v_pk_mul_f32 v[12:13], v[190:191], v[12:13]
	v_pk_add_f32 v[172:173], v[140:141], 1.0 op_sel_hi:[1,0]
	v_pk_fma_f32 v[12:13], v[172:173], v[12:13], v[108:109]
	v_pk_mul_f32 v[14:15], v[192:193], v[14:15]
	v_pk_add_f32 v[174:175], v[142:143], 1.0 op_sel_hi:[1,0]
	v_pk_fma_f32 v[14:15], v[174:175], v[14:15], v[110:111]
	v_cvt_pk_bf16_f32 v168, v12, v13
	v_cvt_pk_bf16_f32 v169, v14, v15
	global_store_dwordx2 v210, v[168:169], s[8:9] offset:1536
	s_nop 0
	v_pk_mul_f32 v[16:17], v[194:195], v[16:17]
	v_pk_add_f32 v[172:173], v[144:145], 1.0 op_sel_hi:[1,0]
	v_pk_fma_f32 v[16:17], v[172:173], v[16:17], v[112:113]
	v_pk_mul_f32 v[18:19], v[196:197], v[18:19]
	v_pk_add_f32 v[174:175], v[146:147], 1.0 op_sel_hi:[1,0]
	v_pk_fma_f32 v[18:19], v[174:175], v[18:19], v[114:115]
	v_cvt_pk_bf16_f32 v168, v16, v17
	v_cvt_pk_bf16_f32 v169, v18, v19
	global_store_dwordx2 v210, v[168:169], s[8:9] offset:2048
	s_nop 0
	v_pk_mul_f32 v[20:21], v[198:199], v[20:21]
	v_pk_add_f32 v[172:173], v[148:149], 1.0 op_sel_hi:[1,0]
	v_pk_fma_f32 v[20:21], v[172:173], v[20:21], v[116:117]
	v_pk_mul_f32 v[22:23], v[200:201], v[22:23]
	v_pk_add_f32 v[174:175], v[150:151], 1.0 op_sel_hi:[1,0]
	v_pk_fma_f32 v[22:23], v[174:175], v[22:23], v[118:119]
	v_cvt_pk_bf16_f32 v168, v20, v21
	v_cvt_pk_bf16_f32 v169, v22, v23
	global_store_dwordx2 v210, v[168:169], s[8:9] offset:2560
	s_nop 0
	v_pk_mul_f32 v[24:25], v[202:203], v[24:25]
	v_pk_add_f32 v[172:173], v[152:153], 1.0 op_sel_hi:[1,0]
	v_pk_fma_f32 v[24:25], v[172:173], v[24:25], v[120:121]
	v_pk_mul_f32 v[26:27], v[204:205], v[26:27]
	v_pk_add_f32 v[174:175], v[154:155], 1.0 op_sel_hi:[1,0]
	v_pk_fma_f32 v[26:27], v[174:175], v[26:27], v[122:123]
	v_cvt_pk_bf16_f32 v168, v24, v25
	v_cvt_pk_bf16_f32 v169, v26, v27
	global_store_dwordx2 v210, v[168:169], s[8:9] offset:3072
	s_nop 0
	v_pk_mul_f32 v[28:29], v[206:207], v[28:29]
	v_pk_add_f32 v[172:173], v[156:157], 1.0 op_sel_hi:[1,0]
	v_pk_fma_f32 v[28:29], v[172:173], v[28:29], v[124:125]
	v_pk_mul_f32 v[30:31], v[208:209], v[30:31]
	v_pk_add_f32 v[174:175], v[158:159], 1.0 op_sel_hi:[1,0]
	v_pk_fma_f32 v[30:31], v[174:175], v[30:31], v[126:127]
	v_cvt_pk_bf16_f32 v168, v28, v29
	v_cvt_pk_bf16_f32 v169, v30, v31
	global_store_dwordx2 v210, v[168:169], s[8:9] offset:3584
	s_nop 0
	s_mov_b32 s2, s3
	s_mov_b32 s3, s101
	s_xor_b32 s100, s100, 0x100
	s_cmpk_lt_i32 s2, 0x2400
	s_cbranch_scc0 .Lnrm_p1_exit
	s_cmpk_lt_i32 s3, 0x2400
	s_cbranch_scc1 .Lnrm_p1_w16
	s_waitcnt vmcnt(8)
	s_branch .Lnrm_p1_top
.Lnrm_p1_w16:
	s_waitcnt vmcnt(16)
	s_branch .Lnrm_p1_top

.Lnrm_p7_nopart:
	s_bitcmp1_b32 s100, 0
	s_cselect_b32 s8, 4, s4
	v_readlane_b32 s10, v254, 53
	v_readlane_b32 s11, v254, 54
	s_mul_i32 s8, s8, 0xc000
	s_add_u32 s10, s10, s8
	s_addc_u32 s11, s11, 0
	s_add_u32 s12, s10, 0x7000
	s_addc_u32 s13, s11, 0
	global_load_dwordx4 v[96:99], v176, s[12:13] offset:-4096
	global_load_dwordx4 v[100:103], v176, s[12:13] offset:-3072
	global_load_dwordx4 v[104:107], v176, s[12:13] offset:-2048
	global_load_dwordx4 v[108:111], v176, s[12:13] offset:-1024
	global_load_dwordx4 v[112:115], v176, s[12:13] offset:0
	global_load_dwordx4 v[116:119], v176, s[12:13] offset:1024
	global_load_dwordx4 v[120:123], v176, s[12:13] offset:2048
	global_load_dwordx4 v[124:127], v176, s[12:13] offset:3072
	s_add_u32 s12, s10, 0x9000
	s_addc_u32 s13, s11, 0
	global_load_dwordx4 v[128:131], v176, s[12:13] offset:-4096
	global_load_dwordx4 v[132:135], v176, s[12:13] offset:-3072
	global_load_dwordx4 v[136:139], v176, s[12:13] offset:-2048
	global_load_dwordx4 v[140:143], v176, s[12:13] offset:-1024
	global_load_dwordx4 v[144:147], v176, s[12:13] offset:0
	global_load_dwordx4 v[148:151], v176, s[12:13] offset:1024
	global_load_dwordx4 v[152:155], v176, s[12:13] offset:2048
	global_load_dwordx4 v[156:159], v176, s[12:13] offset:3072
	s_mov_b32 s101, s3
.Lnrm_p7_adv2:
	s_add_i32 s101, s101, s88
	s_cmpk_lt_i32 s101, 0x2400
	s_cbranch_scc0 .Lnrm_p7_advd2
	v_readlane_b32 s12, v255, 19
	s_cmp_eq_u32 s12, 0
	s_cbranch_scc1 .Lnrm_p7_advd2
	s_mul_hi_i32 s12, s101, 0x38e38e39
	s_lshr_b32 s13, s12, 31
	s_ashr_i32 s12, s12, 9
	s_add_i32 s12, s12, s13
	s_mul_i32 s13, s12, 0xfffff700
	s_add_i32 s13, s101, s13
	s_cmpk_lt_i32 s13, 0x100
	s_cbranch_scc1 .Lnrm_p7_adv2
